# sample_ml: output-gate load hoisted to job top, state stores no longer drained before the tail / at next job top
# speedup vs baseline: 1.0204x; 1.0035x over previous
; __device__ __forceinline__ float bf_lo(unsigned u) { return __uint_as_float(u << 16); }
; __device__ __forceinline__ float bf_hi(unsigned u) { return __uint_as_float(u & 0xffff0000u); }
; __device__ __forceinline__ float logsig_f(float x) { return fminf(x, 0.f) - log1pf(__expf(-fabsf(x))); }
; __device__ __forceinline__ void sample_ml(const Params& p, unsigned char* smem, int job) {
;     ...
;     {
;         const int t = tid >> 6, c = tid & 63;
;         const size_t r = (size_t)(rowb + t) * N1P;
;         const unsigned qq = *(const unsigned*)(U + r + UC_Q + h * 128 + 2 * c), kk = *(const unsigned*)(U + r + UC_K + h * 128 + 2 * c);
;         const u32x2 vv = *(const u32x2*)(U + r + UC_V + h * 256 + 4 * c);
;         qs[t * 128 + 2 * c] = bf_lo(qq); qs[t * 128 + 2 * c + 1] = bf_hi(qq);
;         ks[t * 128 + 2 * c] = bf_lo(kk) * 0.08838834764831845f; ks[t * 128 + 2 * c + 1] = bf_hi(kk) * 0.08838834764831845f;
;         *(f32x4*)(vs + t * 256 + 4 * c) = (f32x4){bf_lo(vv[0]), bf_hi(vv[0]), bf_lo(vv[1]), bf_hi(vv[1])};
;         if (tid < 8) { sig[tid] = SF[(size_t)(rowb + tid) * 64 + 32 + h] + p.in[17][h]; slf[tid] = logsig_f(SF[(size_t)(rowb + tid) * 64 + 40 + h] + p.in[18][h]); }
;         if (tid >= 128 && tid < 256) n0v[tid - 128] = p.in[5][(size_t)(b * 8 + h) * 128 + tid - 128];
;     }
;     const int v4 = lane, dg = wid;
;     const size_t coff = ((size_t)(b * 8 + h) * 128 + dg * 16) * 256 + v4 * 4;
;     f32x4 c0[16];
; #pragma unroll
;     for (int i = 0; i < 16; ++i) c0[i] = __builtin_nontemporal_load((const f32x4*)(p.in[4] + coff + (size_t)i * 256));
;     ...
;         const u32x2 og = *(const u32x2*)(U + (size_t)(rowb + t) * N1P + UC_O + h * 256 + lane * 4);
.LBB0_715:
	v_mov_b32_e32 v116, v151
	s_and_b32 s0, s2, -8
	s_add_i32 s29, s0, 0x2000
	v_ashrrev_i32_e32 v10, 6, v116
	s_and_b32 s28, s2, 7
	v_add_u32_e32 v6, s29, v10
	s_waitcnt lgkmcnt(0)
	v_mov_b64_e32 v[4:5], s[18:19]
	v_and_b32_e32 v132, 63, v116
	v_mad_i64_i32 v[4:5], s[4:5], v6, s45, v[4:5]
	s_lshl_b32 s96, s28, 8
	v_lshl_add_u64 v[6:7], v[4:5], 0, s[96:97]
	v_lshlrev_b32_e32 v148, 2, v132
	v_lshl_add_u64 v[6:7], v[6:7], 0, v[148:149]
	s_movk_i32 s1, 0x2000
	v_add_co_u32_e32 v6, vcc, s1, v6
	s_lshl_b32 s4, s28, 9
	s_nop 0
	v_addc_co_u32_e32 v7, vcc, 0, v7, vcc
	s_mov_b32 s5, s97
	global_load_dword v11, v[6:7], off offset:1088
	global_load_dword v13, v[6:7], off offset:3136
	v_lshl_add_u64 v[4:5], v[4:5], 0, s[4:5]
	v_lshlrev_b32_e32 v6, 3, v132
	v_mov_b32_e32 v7, v149
	v_lshl_add_u64 v[4:5], v[4:5], 0, v[6:7]
	s_movk_i32 s1, 0x3000
	v_add_co_u32_e32 v4, vcc, s1, v4
	v_lshl_or_b32 v6, v10, 9, v6
	s_nop 0
	v_addc_co_u32_e32 v5, vcc, 0, v5, vcc
	global_load_dwordx2 v[8:9], v[4:5], off offset:1088
	v_readfirstlane_b32 s1, v10
	s_nop 0
	s_add_i32 s4, s1, s29
	s_mul_hi_i32 s5, s4, 0x5600
	s_mul_i32 s4, s4, 0x5600
	s_add_u32 s4, s18, s4
	s_addc_u32 s5, s19, s5
	s_lshl_b32 s6, s96, 1
	s_add_u32 s4, s4, s6
	s_addc_u32 s5, s5, 0
	s_add_u32 s4, s4, 0x4000
	s_addc_u32 s5, s5, 0
	v_lshlrev_b32_e32 v218, 1, v148
	v_mov_b32_e32 v219, v149
	v_lshl_add_u64 v[218:219], s[4:5], 0, v[218:219]
	global_load_dwordx2 v[220:221], v[218:219], off offset:1120
	s_ashr_i32 s3, s2, 31
	s_lshl_b32 s1, s1, 4
	s_lshl_b64 s[4:5], s[2:3], 7
	s_add_u32 s6, s4, s1
	s_addc_u32 s7, s5, 0
	s_lshl_b64 s[6:7], s[6:7], 8
	v_readlane_b32 s4, v254, 51
	v_readlane_b32 s5, v254, 52
	v_mov_b32_e32 v215, s7
	v_or_b32_e32 v214, s6, v148
	s_movk_i32 s6, 0x2000
	s_mov_b32 s7, 0
	v_lshl_add_u64 v[214:215], v[214:215], 2, s[4:5]
	v_lshl_add_u64 v[216:217], v[214:215], 0, s[6:7]
	global_load_dwordx4 v[96:99], v[214:215], off nt
	global_load_dwordx4 v[92:95], v[214:215], off offset:1024 nt
	global_load_dwordx4 v[88:91], v[214:215], off offset:2048 nt
	global_load_dwordx4 v[84:87], v[214:215], off offset:3072 nt
	global_load_dwordx4 v[76:79], v[216:217], off offset:-3072 nt
	global_load_dwordx4 v[72:75], v[216:217], off offset:-2048 nt
	global_load_dwordx4 v[80:83], v[216:217], off offset:-4096 nt
	global_load_dwordx4 v[64:67], v[216:217], off nt
	global_load_dwordx4 v[60:63], v[216:217], off offset:1024 nt
	global_load_dwordx4 v[56:59], v[216:217], off offset:2048 nt
	global_load_dwordx4 v[52:55], v[216:217], off offset:3072 nt
	global_load_dwordx4 v[68:71], v[216:217], off offset:-1024 nt
	v_lshlrev_b32_e32 v4, 10, v10
	v_lshlrev_b32_e32 v5, 4, v132
	v_cmp_gt_i32_e32 vcc, 8, v116
	v_readfirstlane_b32 s30, v10
	v_add3_u32 v14, 0, v4, v5
	v_add_u32_e32 v15, 0, v6
	v_lshl_add_u32 v133, v116, 2, 0
	s_waitcnt vmcnt(15)
	v_lshlrev_b32_e32 v10, 16, v11
	s_waitcnt vmcnt(14)
	v_lshlrev_b32_e32 v12, 16, v13
	v_and_b32_e32 v13, 0xffff0000, v13
	v_and_b32_e32 v11, 0xffff0000, v11
	s_waitcnt vmcnt(13)
	v_lshlrev_b32_e32 v4, 16, v8
	v_and_b32_e32 v5, 0xffff0000, v8
	v_lshlrev_b32_e32 v6, 16, v9
	v_and_b32_e32 v7, 0xffff0000, v9
	v_pk_mul_f32 v[8:9], v[12:13], s[90:91] op_sel_hi:[1,0]
	ds_write2st64_b64 v15, v[10:11], v[8:9] offset1:8
	ds_write_b128 v14, v[4:7] offset:8192
	s_and_saveexec_b64 s[4:5], vcc
	s_cbranch_execz .LBB0_717
; __device__ __forceinline__ float logsig_f(float x) { return fminf(x, 0.f) - log1pf(__expf(-fabsf(x))); }
; __device__ __forceinline__ void sample_ml(const Params& p, unsigned char* smem, int job) {
;     ...
;         if (tid < 8) { sig[tid] = SF[(size_t)(rowb + tid) * 64 + 32 + h] + p.in[17][h]; slf[tid] = logsig_f(SF[(size_t)(rowb + tid) * 64 + 40 + h] + p.in[18][h]); }
	v_add_u32_e32 v4, s29, v116
	v_ashrrev_i32_e32 v5, 31, v4
	v_lshlrev_b64 v[4:5], 8, v[4:5]
	v_lshl_add_u64 v[4:5], s[20:21], 0, v[4:5]
	s_lshl_b32 s6, s28, 2
	s_mov_b32 s7, s97
	v_readlane_b32 s56, v255, 11
	v_lshl_add_u64 v[6:7], v[4:5], 0, s[6:7]
	v_mov_b32_e32 v5, s6
	v_readlane_b32 s58, v255, 13
	v_readlane_b32 s59, v255, 14
	global_load_dword v4, v[6:7], off offset:128
	v_readlane_b32 s60, v255, 15
	v_readlane_b32 s61, v255, 16
	s_mov_b32 s1, 0xbfb8aa3b
	s_mov_b32 s6, 0x3f317218
	global_load_dword v8, v5, s[58:59]
	s_nop 0
	global_load_dword v6, v[6:7], off offset:160
	s_nop 0
	global_load_dword v5, v5, s[60:61]
	v_readlane_b32 s57, v255, 12
	v_readlane_b32 s62, v255, 17
	v_readlane_b32 s63, v255, 18
	v_readlane_b32 s64, v255, 19
	v_readlane_b32 s65, v255, 20
	v_readlane_b32 s66, v255, 21
	v_readlane_b32 s67, v255, 22
	v_readlane_b32 s68, v255, 23
	v_readlane_b32 s69, v255, 24
	v_readlane_b32 s70, v255, 25
	v_readlane_b32 s71, v255, 26
	s_waitcnt vmcnt(2)
	v_add_f32_e32 v4, v4, v8
	s_waitcnt vmcnt(0)
	v_add_f32_e32 v6, v6, v5
	v_min_f32_e32 v5, 0, v6
	v_mul_f32_e64 v6, |v6|, s1
	v_exp_f32_e32 v6, v6
	s_mov_b32 s1, 0x3f2aaaab
	v_add_f32_e32 v7, 1.0, v6
	v_add_f32_e32 v8, -1.0, v7
	v_sub_f32_e32 v9, v8, v7
	v_add_f32_e32 v9, 1.0, v9
	v_sub_f32_e32 v8, v6, v8
	v_add_f32_e32 v10, v8, v9
	v_frexp_mant_f32_e32 v8, v7
	v_cmp_gt_f32_e32 vcc, s1, v8
	v_cvt_f64_f32_e32 v[8:9], v7
	v_frexp_exp_i32_f64_e32 v8, v[8:9]
	v_subbrev_co_u32_e32 v8, vcc, 0, v8, vcc
	v_sub_u32_e32 v9, 0, v8
	v_ldexp_f32 v7, v7, v9
	v_ldexp_f32 v9, v10, v9
	v_add_f32_e32 v10, -1.0, v7
	v_add_f32_e32 v11, 1.0, v10
	v_sub_f32_e32 v11, v7, v11
	v_add_f32_e32 v11, v9, v11
	v_add_f32_e32 v12, v10, v11
	v_sub_f32_e32 v10, v12, v10
	v_sub_f32_e32 v10, v11, v10
	v_add_f32_e32 v11, 1.0, v7
	v_add_f32_e32 v13, -1.0, v11
	v_sub_f32_e32 v7, v7, v13
	v_add_f32_e32 v7, v9, v7
	v_add_f32_e32 v9, v11, v7
	v_sub_f32_e32 v11, v9, v11
	v_sub_f32_e32 v7, v7, v11
	v_rcp_f32_e32 v11, v9
	v_cvt_f32_i32_e32 v8, v8
	s_mov_b32 s1, 0x7f800000
	v_cmp_neq_f32_e32 vcc, s1, v6
	v_mul_f32_e32 v13, v12, v11
	v_mul_f32_e32 v14, v9, v13
	v_fma_f32 v15, v13, v9, -v14
	v_fmac_f32_e32 v15, v13, v7
	v_add_f32_e32 v16, v14, v15
	v_sub_f32_e32 v17, v12, v16
	v_sub_f32_e32 v12, v12, v17
	v_sub_f32_e32 v14, v16, v14
	v_sub_f32_e32 v12, v12, v16
	v_add_f32_e32 v10, v10, v12
	v_sub_f32_e32 v12, v14, v15
	v_add_f32_e32 v10, v12, v10
	v_add_f32_e32 v12, v17, v10
	v_mul_f32_e32 v14, v11, v12
	v_mul_f32_e32 v15, v9, v14
	v_fma_f32 v9, v14, v9, -v15
	v_fmac_f32_e32 v9, v14, v7
	v_sub_f32_e32 v7, v17, v12
	v_add_f32_e32 v7, v10, v7
	v_add_f32_e32 v10, v15, v9
	v_sub_f32_e32 v16, v12, v10
	v_sub_f32_e32 v12, v12, v16
	v_sub_f32_e32 v15, v10, v15
	v_sub_f32_e32 v10, v12, v10
	v_add_f32_e32 v7, v7, v10
	v_sub_f32_e32 v9, v15, v9
	v_add_f32_e32 v7, v9, v7
	v_add_f32_e32 v9, v13, v14
	v_add_f32_e32 v7, v16, v7
	v_sub_f32_e32 v10, v9, v13
	v_mul_f32_e32 v7, v11, v7
	v_sub_f32_e32 v10, v14, v10
	v_add_f32_e32 v7, v10, v7
	v_mul_f32_e32 v13, 0x3f317218, v8
	v_add_f32_e32 v10, v9, v7
	v_fma_f32 v14, v8, s6, -v13
	v_mul_f32_e32 v11, v10, v10
	v_fmac_f32_e32 v14, 0xb102e308, v8
	v_sub_f32_e32 v8, v10, v9
	v_fmamk_f32 v12, v11, 0x3e9b6dac, v150
	v_sub_f32_e32 v7, v7, v8
	v_add_f32_e32 v8, v13, v14
	v_fmaak_f32 v12, v11, v12, 0x3f2aaada
	v_sub_f32_e32 v9, v8, v13
	v_ldexp_f32 v13, v10, 1
	v_mul_f32_e32 v10, v10, v11
	v_mul_f32_e32 v10, v10, v12
	v_add_f32_e32 v11, v13, v10
	v_sub_f32_e32 v12, v11, v13
	v_ldexp_f32 v7, v7, 1
	v_sub_f32_e32 v10, v10, v12
	v_add_f32_e32 v7, v7, v10
	v_add_f32_e32 v10, v11, v7
	v_sub_f32_e32 v11, v10, v11
	v_sub_f32_e32 v7, v7, v11
	v_add_f32_e32 v11, v8, v10
	v_sub_f32_e32 v12, v11, v8
	v_sub_f32_e32 v13, v11, v12
	v_sub_f32_e32 v9, v14, v9
	v_sub_f32_e32 v8, v8, v13
	v_sub_f32_e32 v10, v10, v12
	v_add_f32_e32 v8, v10, v8
	v_add_f32_e32 v10, v9, v7
	v_sub_f32_e32 v12, v10, v9
	v_sub_f32_e32 v13, v10, v12
	v_sub_f32_e32 v9, v9, v13
	v_sub_f32_e32 v7, v7, v12
	v_add_f32_e32 v8, v10, v8
	v_add_f32_e32 v7, v7, v9
	v_add_f32_e32 v9, v11, v8
	v_sub_f32_e32 v10, v9, v11
	v_sub_f32_e32 v8, v8, v10
	v_add_f32_e32 v7, v7, v8
	v_add_f32_e32 v7, v9, v7
	v_cndmask_b32_e32 v7, v210, v7, vcc
	v_cmp_ngt_f32_e32 vcc, -1.0, v6
	s_mov_b32 s1, 0x33800000
	s_nop 0
	v_cndmask_b32_e32 v7, v211, v7, vcc
	v_cmp_neq_f32_e32 vcc, -1.0, v6
	s_nop 1
	v_cndmask_b32_e32 v7, v212, v7, vcc
	v_cmp_lt_f32_e64 vcc, |v6|, s1
	s_nop 1
	v_cndmask_b32_e32 v6, v7, v6, vcc
	v_sub_f32_e32 v5, v5, v6
	v_add_u32_e32 v6, 0x4000, v133
	ds_write2_b32 v6, v4, v5 offset0:64 offset1:72

; __device__ __forceinline__ unsigned pack2(float lo, float hi) { unsigned r; asm("v_cvt_pk_bf16_f32 %0, %1, %2" : "=v"(r) : "v"(lo), "v"(hi)); return r; }
; __device__ __forceinline__ float bf_lo(unsigned u) { return __uint_as_float(u << 16); }
; __device__ __forceinline__ float bf_hi(unsigned u) { return __uint_as_float(u & 0xffff0000u); }
; __device__ __forceinline__ float sigm_f(float x) { const float d = 1.f + __expf(fminf(-x, 80.f)); float r = __builtin_amdgcn_rcpf(d); return r * (2.f - d * r); }
; __device__ __forceinline__ void sample_ml(const Params& p, unsigned char* smem, int job) {
;     ...
;     {
;         const int t = wid;
;         float Mt = 0.f, Ft = 0.f;
; #pragma unroll
;         for (int q = 0; q < 8; ++q) { Mt = (t == q) ? M[q] : Mt; Ft = (t == q) ? F[q] : Ft; }
;         f32x4 numc = {0.f, 0.f, 0.f, 0.f};
; #pragma unroll
;         for (int q = 0; q < 8; ++q) numc += *(const f32x4*)(red + (q * 8 + t) * 256 + lane * 4);
;         const float et = __expf(mp - Mt);
;         float den = et * qnv[t];
;         f32x4 intra = {0.f, 0.f, 0.f, 0.f};
; #pragma unroll
;         for (int s = 0; s < 8; ++s) {
;             if (s <= t) { const float w = __expf(gg[s] - Mt) * QK[t * 8 + s]; den += w; intra += w * vv[s]; }
;         }
;         const float dd = fmaxf(fabsf(den), __expf(-(Ft + Mt)));
;         const f32x4 hv = (et * numc + intra) * (1.f / dd);
;         float ss = hv[0] * hv[0] + hv[1] * hv[1] + hv[2] * hv[2] + hv[3] * hv[3];
;         ss = wave_sum(ss);
;         const u32x2 og = *(const u32x2*)(U + (size_t)(rowb + t) * N1P + UC_O + h * 256 + lane * 4);
;         *(u32x2*)(MIX + (size_t)(rowb + t) * MIXW + 2048 + h * 256 + lane * 4) =
;             (u32x2){pack2(hv[0] * sigm_f(bf_lo(og[0])), hv[1] * sigm_f(bf_hi(og[0]))), pack2(hv[2] * sigm_f(bf_lo(og[1])), hv[3] * sigm_f(bf_hi(og[1])))};
;         if (lane < 4) ((float*)(p.ws + WS_SSQM))[(size_t)(rowb + t) * 32 + h * 4 + lane] = lane == 0 ? ss : 0.f;
;         if (lane == 0) ((float*)(p.ws + WS_DD))[(size_t)(rowb + t) * 8 + h] = 1.f;
.LBB0_743:
	v_cndmask_b32_e32 v16, 0, v140, vcc
	v_cndmask_b32_e64 v16, v16, v141, s[0:1]
	v_pk_add_f32 v[18:19], v[64:65], 0 op_sel_hi:[1,0]
	v_cndmask_b32_e64 v16, v16, v142, s[4:5]
	v_pk_add_f32 v[18:19], v[18:19], v[60:61]
	v_cndmask_b32_e64 v16, v16, v143, s[6:7]
	v_pk_add_f32 v[18:19], v[18:19], v[56:57]
	v_cndmask_b32_e64 v16, v16, v144, s[8:9]
	v_pk_add_f32 v[18:19], v[18:19], v[52:53]
	v_cndmask_b32_e64 v16, v16, v145, s[10:11]
	v_pk_add_f32 v[18:19], v[18:19], v[48:49]
	v_cndmask_b32_e64 v16, v16, v146, s[12:13]
	v_pk_add_f32 v[12:13], v[18:19], v[12:13]
	v_cndmask_b32_e64 v20, v16, v147, s[14:15]
	v_pk_add_f32 v[16:17], v[66:67], 0 op_sel_hi:[1,0]
	v_pk_add_f32 v[8:9], v[12:13], v[8:9]
	v_pk_add_f32 v[16:17], v[16:17], v[62:63]
	v_pk_add_f32 v[4:5], v[8:9], v[4:5]
	v_add_f32_e32 v8, v20, v69
	v_pk_add_f32 v[16:17], v[16:17], v[58:59]
	v_mul_f32_e32 v8, 0xbfb8aa3b, v8
	v_pk_add_f32 v[16:17], v[16:17], v[54:55]
	v_exp_f32_e32 v8, v8
	v_pk_add_f32 v[16:17], v[16:17], v[50:51]
	v_max_f32_e64 v9, |v70|, |v70|
	v_pk_add_f32 v[14:15], v[16:17], v[14:15]
	s_nop 0
	v_pk_add_f32 v[10:11], v[14:15], v[10:11]
	s_nop 0
	v_pk_add_f32 v[6:7], v[10:11], v[6:7]
	v_max_f32_e32 v10, v9, v8
	v_pk_fma_f32 v[8:9], v[68:69], v[4:5], v[44:45] op_sel_hi:[0,1,1]
	v_pk_fma_f32 v[4:5], v[68:69], v[6:7], v[46:47] op_sel_hi:[0,1,1]
	v_div_scale_f32 v6, s[0:1], v10, v10, 1.0
	v_rcp_f32_e32 v7, v6
	s_add_i32 s0, s30, s29
	s_ashr_i32 s1, s0, 31
	s_mul_i32 s4, s0, 0x5600
	v_fma_f32 v11, -v6, v7, 1.0
	v_fmac_f32_e32 v7, v11, v7
	v_div_scale_f32 v11, vcc, 1.0, v10, 1.0
	v_mul_f32_e32 v12, v11, v7
	v_fma_f32 v13, -v6, v12, v11
	v_fmac_f32_e32 v12, v13, v7
	v_fma_f32 v6, -v6, v12, v11
	v_div_fmas_f32 v6, v6, v7, v12
	v_div_fixup_f32 v6, v6, v10, 1.0
	v_pk_mul_f32 v[4:5], v[4:5], v[6:7] op_sel_hi:[1,0]
	v_pk_mul_f32 v[6:7], v[8:9], v[6:7] op_sel_hi:[1,0]
	s_mul_hi_i32 s3, s0, 0x5600
	v_mul_f32_e32 v8, v7, v7
	v_fmac_f32_e32 v8, v6, v6
	v_fmac_f32_e32 v8, v4, v4
	v_fmac_f32_e32 v8, v5, v5
	ds_bpermute_b32 v9, v137, v8
	s_add_u32 s4, s18, s4
	s_addc_u32 s5, s19, s3
	s_lshl_b32 s3, s96, 1
	s_add_u32 s4, s4, s3
	s_waitcnt lgkmcnt(0)
	v_add_f32_e32 v8, v8, v9
	ds_bpermute_b32 v9, v138, v8
	s_addc_u32 s5, s5, 0
	s_waitcnt lgkmcnt(0)
	v_add_f32_e32 v8, v8, v9
	ds_bpermute_b32 v9, v139, v8
	s_waitcnt lgkmcnt(0)
	v_add_f32_e32 v8, v8, v9
	ds_bpermute_b32 v9, v136, v8
	s_waitcnt lgkmcnt(0)
	v_add_f32_e32 v8, v8, v9
	ds_bpermute_b32 v9, v135, v8
	s_waitcnt lgkmcnt(0)
	v_add_f32_e32 v12, v8, v9
	v_lshlrev_b32_e32 v8, 1, v148
	v_mov_b32_e32 v9, v149
	v_lshl_add_u64 v[10:11], s[4:5], 0, v[8:9]
	s_movk_i32 s4, 0x4000
	v_add_co_u32_e32 v10, vcc, s4, v10
	s_lshl_b64 s[4:5], s[0:1], 13
	s_nop 0
	v_addc_co_u32_e32 v11, vcc, 0, v11, vcc
	s_add_u32 s4, s82, s4
	s_addc_u32 s5, s83, s5
	s_add_u32 s4, s4, s3
	ds_bpermute_b32 v13, v134, v12
	s_addc_u32 s5, s5, 0
	v_mov_b32_e32 v10, v220
	v_mov_b32_e32 v11, v221
	v_lshlrev_b32_e32 v14, 16, v10
	v_max_f32_e64 v14, -v14, -v14
	v_min_f32_e32 v14, 0x42a00000, v14
	v_mul_f32_e32 v14, 0x3fb8aa3b, v14
	v_exp_f32_e32 v14, v14
	v_and_b32_e32 v10, 0xffff0000, v10
	v_max_f32_e64 v10, -v10, -v10
	v_min_f32_e32 v10, 0x42a00000, v10
	v_add_f32_e32 v14, 1.0, v14
	v_rcp_f32_e32 v15, v14
	v_mul_f32_e32 v10, 0x3fb8aa3b, v10
	v_exp_f32_e32 v10, v10
	v_fma_f32 v14, -v14, v15, 2.0
	v_mul_f32_e32 v14, v15, v14
	v_add_f32_e32 v10, 1.0, v10
	v_mul_f32_e32 v6, v6, v14
	v_rcp_f32_e32 v14, v10
	s_nop 0
	v_fma_f32 v10, -v10, v14, 2.0
	v_mul_f32_e32 v10, v14, v10
	v_mul_f32_e32 v7, v7, v10
	v_cvt_pk_bf16_f32 v6, v6, v7
	v_lshlrev_b32_e32 v7, 16, v11
	v_max_f32_e64 v7, -v7, -v7
	v_min_f32_e32 v7, 0x42a00000, v7
	v_mul_f32_e32 v7, 0x3fb8aa3b, v7
	v_exp_f32_e32 v7, v7
	s_nop 0
	v_add_f32_e32 v7, 1.0, v7
	v_rcp_f32_e32 v10, v7
	s_nop 0
	v_fma_f32 v7, -v7, v10, 2.0
	v_mul_f32_e32 v7, v10, v7
	v_mul_f32_e32 v4, v4, v7
	v_and_b32_e32 v7, 0xffff0000, v11
	v_max_f32_e64 v7, -v7, -v7
	v_min_f32_e32 v7, 0x42a00000, v7
	v_mul_f32_e32 v7, 0x3fb8aa3b, v7
	v_exp_f32_e32 v7, v7
	s_nop 0
	v_add_f32_e32 v7, 1.0, v7
	v_rcp_f32_e32 v10, v7
	s_nop 0
	v_fma_f32 v7, -v7, v10, 2.0
	v_mul_f32_e32 v7, v10, v7
	v_mul_f32_e32 v5, v5, v7
	v_cvt_pk_bf16_f32 v7, v4, v5
	v_lshl_add_u64 v[4:5], s[4:5], 0, v[8:9]
	v_add_co_u32_e32 v4, vcc, 0xa201000, v4
	s_nop 1
	v_addc_co_u32_e32 v5, vcc, 0, v5, vcc
	v_cmp_gt_u32_e32 vcc, 4, v132
	global_store_dwordx2 v[4:5], v[6:7], off
	s_and_saveexec_b64 s[4:5], vcc
	s_cbranch_execz .LBB0_745
	s_lshl_b64 s[6:7], s[0:1], 7
	s_add_u32 s3, s24, s6
	s_addc_u32 s7, s25, s7
	s_lshl_b32 s6, s28, 4
	s_waitcnt lgkmcnt(0)
	v_add_f32_e32 v4, v12, v13
	s_add_u32 s6, s3, s6
	v_cndmask_b32_e64 v4, 0, v4, s[16:17]
	s_addc_u32 s7, s7, 0
	global_store_dword v148, v4, s[6:7]
